# ret_r2 state scan moved from the serial head of phase 4 into the two role-less waves of the RWKV scan loop
# speedup vs baseline: 1.0041x; 1.0041x over previous
.LBB0_739:
	s_or_b64 exec, exec, s[4:5]
	v_readlane_b32 s6, v254, 5
	v_readlane_b32 s7, v254, 6
	s_waitcnt lgkmcnt(0)
	v_mov_b32_e32 v0, v226
	v_readlane_b32 s0, v254, 0
	s_barrier
	s_nop 0
	v_add_u32_e32 v52, s0, v0
	s_mov_b32 s0, 0x20000
	v_cmp_gt_i32_e32 vcc, s0, v52
	s_and_saveexec_b64 s[4:5], vcc
	s_branch .LBB0_748

.LBB0_751:
	v_mov_b32_e32 v31, v226
	s_nop 0
	v_and_b32_e32 v30, 63, v31
	v_ashrrev_i32_e32 v32, 6, v31
	v_cmp_eq_u32_e32 vcc, 0, v30
	s_and_saveexec_b64 s[6:7], vcc
	s_cbranch_execz .LBB0_753
	s_getreg_b32 s0, hwreg(HW_REG_HW_ID, 4, 2)
	s_waitcnt vmcnt(6)
	v_lshl_add_u32 v0, v32, 2, 0
	s_and_b32 s0, s0, 3
	v_add_u32_e32 v0, 0x24010, v0
	v_mov_b32_e32 v1, s0
	ds_write_b32 v0, v1
	v_mov_b32_e32 v2, 0x24030
	v_mov_b32_e32 v3, 0
	ds_write_b32 v2, v3

.LBB0_783:
	s_or_b64 exec, exec, s[10:11]
	v_cmp_gt_u32_e32 vcc, 64, v31
	v_cmp_eq_u32_e64 s[10:11], s4, v32
	s_or_b64 s[26:27], vcc, s[10:11]
	s_and_saveexec_b64 s[10:11], s[26:27]
	s_setprio 3
	s_or_b64 exec, exec, s[10:11]
	s_lshl_b32 s0, s94, 9
	s_and_b32 s0, s0, 0x3000
	s_mulk_i32 s0, 0x4200
	s_add_u32 s0, s24, s0
	s_addc_u32 s1, s25, 0
	s_lshl_b32 s4, s93, 8
	s_and_b32 s4, s4, 0x700
	s_add_u32 s4, s0, s4
	s_addc_u32 s5, s1, 0
	s_ashr_i32 s0, s93, 2
	s_and_b32 s30, s0, -8
	s_ashr_i32 s31, s30, 31
	s_lshl_b64 s[0:1], s[30:31], 2
	s_add_u32 s0, s4, s0
	v_cndmask_b32_e64 v28, 4, 0, vcc
	s_addc_u32 s1, s5, s1
	v_lshrrev_b32_e32 v29, 4, v30
	s_add_u32 s28, s0, 0x33f1800
	v_and_b32_e32 v32, 15, v31
	v_or_b32_e32 v95, v28, v29
	s_addc_u32 s29, s1, 0
	v_lshlrev_b32_e32 v28, 6, v95
	s_add_i32 s1, 0, 0x18000
	v_lshlrev_b32_e32 v29, 2, v32
	v_add3_u32 v102, s1, v28, v29
	v_mul_lo_u32 v28, v34, 56
	v_sub_u32_e32 v28, v144, v28
	v_cmp_lt_u32_e64 s[10:11], 15, v28
	v_lshlrev_b32_e32 v29, 3, v28
	v_lshlrev_b32_e32 v105, 4, v28
	v_add_u32_e32 v28, 0x100, v144
	v_lshlrev_b32_e32 v97, 4, v32
	v_and_b32_e32 v32, 56, v29
	v_and_b32_e32 v104, 0x1c0, v29
	v_lshrrev_b32_e32 v29, 3, v28
	v_mul_hi_u32 v29, v29, s51
	v_mul_lo_u32 v103, v34, s52
	v_mul_lo_u32 v34, v29, 56
	v_sub_u32_e32 v28, v28, v34
	v_cmp_lt_u32_e64 s[12:13], 15, v28
	v_lshlrev_b32_e32 v34, 3, v28
	v_lshlrev_b32_e32 v108, 4, v28
	v_add_u32_e32 v28, 0x200, v144
	v_mul_lo_u32 v106, v29, s52
	v_lshrrev_b32_e32 v29, 3, v28
	v_mul_hi_u32 v29, v29, s51
	v_and_b32_e32 v35, 56, v34
	v_and_b32_e32 v107, 0x1c0, v34
	v_mul_lo_u32 v34, v29, 56
	v_sub_u32_e32 v28, v28, v34
	v_cmp_lt_u32_e64 s[14:15], 15, v28
	v_lshlrev_b32_e32 v34, 3, v28
	v_lshlrev_b32_e32 v111, 4, v28
	v_add_u32_e32 v28, 0x300, v144
	v_mul_lo_u32 v109, v29, s52
	v_lshrrev_b32_e32 v29, 3, v28
	v_mul_hi_u32 v29, v29, s51
	v_and_b32_e32 v36, 56, v34
	v_and_b32_e32 v110, 0x1c0, v34
	v_mul_lo_u32 v34, v29, 56
	v_sub_u32_e32 v28, v28, v34
	v_cmp_lt_u32_e64 s[16:17], 15, v28
	v_lshlrev_b32_e32 v34, 3, v28
	v_lshlrev_b32_e32 v114, 4, v28
	v_add_u32_e32 v28, 0x400, v144
	v_mul_lo_u32 v112, v29, s52
	v_lshrrev_b32_e32 v29, 3, v28
	v_mul_hi_u32 v29, v29, s51
	v_and_b32_e32 v37, 56, v34
	v_and_b32_e32 v113, 0x1c0, v34
	v_mul_lo_u32 v34, v29, 56
	v_sub_u32_e32 v28, v28, v34
	v_cmp_lt_u32_e64 s[18:19], 15, v28
	v_lshlrev_b32_e32 v34, 3, v28
	v_lshlrev_b32_e32 v117, 4, v28
	v_add_u32_e32 v28, 0x500, v144
	v_mul_lo_u32 v115, v29, s52
	v_lshrrev_b32_e32 v29, 3, v28
	v_mul_hi_u32 v29, v29, s51
	v_and_b32_e32 v38, 56, v34
	v_and_b32_e32 v116, 0x1c0, v34
	v_mul_lo_u32 v34, v29, 56
	v_sub_u32_e32 v28, v28, v34
	v_cmp_lt_u32_e64 s[20:21], 15, v28
	v_lshlrev_b32_e32 v34, 3, v28
	v_lshlrev_b32_e32 v120, 4, v28
	v_add_u32_e32 v28, 0x600, v144
	v_mul_lo_u32 v118, v29, s52
	v_lshrrev_b32_e32 v29, 3, v28
	s_and_b32 s0, s48, 31
	v_mul_hi_u32 v29, v29, s51
	s_mul_i32 s0, s0, 0x380000
	v_and_b32_e32 v39, 56, v34
	v_and_b32_e32 v119, 0x1c0, v34
	v_mul_lo_u32 v34, v29, 56
	v_and_b32_e32 v88, 7, v31
	v_sub_u32_e32 v28, v28, v34
	v_lshlrev_b32_e32 v121, 6, v144
	v_lshlrev_b32_e32 v144, 2, v88
	s_add_u32 s0, s24, s0
	v_lshlrev_b32_e32 v34, 3, v28
	v_add_u32_e32 v125, s1, v121
	v_lshl_add_u64 v[90:91], s[28:29], 0, v[144:145]
	v_add_u32_e32 v144, v33, v30
	s_addc_u32 s1, s25, 0
	v_cmp_lt_u32_e64 s[22:23], 15, v28
	v_and_b32_e32 v40, 56, v34
	v_lshlrev_b32_e32 v124, 4, v28
	v_lshrrev_b32_e32 v28, 3, v144
	v_lshl_add_u64 v[92:93], v[144:145], 4, s[0:1]
	v_mov_b32_e32 v144, v145
	s_mov_b32 s54, 0
	v_mul_lo_u32 v122, v29, s52
	v_and_b32_e32 v123, 0x1c0, v34
	v_subrev_u32_e32 v126, 36, v28
	s_movk_i32 s31, 0xf000
	s_mov_b64 s[34:35], 0
	v_lshlrev_b32_e32 v127, 2, v32
	v_lshlrev_b32_e32 v128, 2, v35
	v_lshlrev_b32_e32 v129, 2, v36
	v_lshlrev_b32_e32 v130, 2, v37
	v_lshlrev_b32_e32 v131, 2, v38
	v_lshlrev_b32_e32 v132, 2, v39
	v_lshlrev_b32_e32 v133, 2, v40
	v_mov_b64_e32 v[32:33], v[144:145]
	v_mov_b64_e32 v[34:35], v[144:145]
	s_or_b64 s[0:1], s[26:27], s[6:7]
	s_cmp_lg_u64 s[0:1], 0
	s_cbranch_scc1 .Lidle_init_done
	s_mov_b64 s[0:1], exec
	s_mov_b64 exec, 1
	v_mov_b32_e32 v68, 0x24030
	v_mov_b32_e32 v69, 1
	ds_add_rtn_u32 v70, v68, v69
	s_waitcnt lgkmcnt(0)
	v_readfirstlane_b32 s4, v70
	s_mov_b64 exec, s[0:1]
	s_and_b32 s4, s4, 1
	s_lshl_b32 s4, s4, 6
	s_lshl_b32 s5, s2, 9
	s_add_i32 s4, s4, s5
	v_and_b32_e32 v66, 63, v226
	v_add_u32_e32 v66, s4, v66
.Lidle_init_done:
	s_and_saveexec_b64 s[0:1], s[26:27]
	s_cbranch_execz .Lscan_init_done
	v_mov_b32_e32 v0, 0
	v_mov_b32_e32 v1, 0
	v_mov_b32_e32 v2, 0
	v_mov_b32_e32 v3, 0
	v_mov_b32_e32 v4, 0
	v_mov_b32_e32 v5, 0
	v_mov_b32_e32 v6, 0
	v_mov_b32_e32 v7, 0
	v_mov_b32_e32 v8, 0
	v_mov_b32_e32 v9, 0
	v_mov_b32_e32 v14, 0
	v_mov_b32_e32 v15, 0
	v_mov_b32_e32 v16, 0
	v_mov_b32_e32 v17, 0
	v_mov_b32_e32 v48, 0
	v_mov_b32_e32 v49, 0
	v_mov_b32_e32 v50, 0
	v_mov_b32_e32 v51, 0
	v_mov_b32_e32 v52, 0
	v_mov_b32_e32 v53, 0
	v_mov_b32_e32 v54, 0
	v_mov_b32_e32 v55, 0
	v_mov_b32_e32 v56, 0
	v_mov_b32_e32 v57, 0
	v_mov_b32_e32 v58, 0
	v_mov_b32_e32 v59, 0
	v_mov_b32_e32 v60, 0
	v_mov_b32_e32 v61, 0
	v_mov_b32_e32 v62, 0
	v_mov_b32_e32 v63, 0
	v_mov_b32_e32 v64, 0
	v_mov_b32_e32 v65, 0
	v_mov_b32_e32 v66, 0
	v_mov_b32_e32 v67, 0
	v_mov_b32_e32 v68, 0
	v_mov_b32_e32 v69, 0
	v_mov_b32_e32 v70, 0
	v_mov_b32_e32 v71, 0
	v_mov_b32_e32 v72, 0
	v_mov_b32_e32 v73, 0
	v_mov_b32_e32 v74, 0
	v_mov_b32_e32 v75, 0
	v_mov_b32_e32 v76, 0
	v_mov_b32_e32 v77, 0
	v_mov_b32_e32 v78, 0
	v_mov_b32_e32 v79, 0
	v_mov_b32_e32 v80, 0
	v_mov_b32_e32 v81, 0
	v_mov_b32_e32 v82, 0
	v_mov_b32_e32 v83, 0
	v_mov_b32_e32 v84, 0
	v_mov_b32_e32 v85, 0
	v_mov_b32_e32 v86, 0
	v_mov_b32_e32 v87, 0
	v_mov_b32_e32 v104, 0
	v_mov_b32_e32 v105, 0
	v_mov_b32_e32 v106, 0
	v_mov_b32_e32 v107, 0
	v_mov_b32_e32 v108, 0
	v_mov_b32_e32 v109, 0
	v_mov_b32_e32 v110, 0
	v_mov_b32_e32 v111, 0
	v_mov_b32_e32 v112, 0
	v_mov_b32_e32 v113, 0
	v_mov_b32_e32 v114, 0
	v_mov_b32_e32 v115, 0
	v_mov_b32_e32 v116, 0
	v_mov_b32_e32 v117, 0
	v_mov_b32_e32 v118, 0
	v_mov_b32_e32 v119, 0
	v_mov_b32_e32 v120, 0
	v_mov_b32_e32 v121, 0
	v_mov_b32_e32 v122, 0
	v_mov_b32_e32 v123, 0

.Lidle_work:
	s_or_b64 exec, exec, s[44:45]
	s_cmp_ge_u32 s54, 16
	s_cbranch_scc1 .LBB0_791
	s_and_b32 s10, s54, 3
	s_lshr_b32 s11, s54, 2
	s_lshl_b32 s11, s11, 7
	s_cmp_eq_u32 s10, 1
	s_cbranch_scc1 .Lidle_p1
	s_cmp_eq_u32 s10, 2
	s_cbranch_scc1 .Lidle_p2
	s_branch .LBB0_791
.Lidle_p1:
	s_add_u32 s12, s24, 0x14bf0000
	s_addc_u32 s13, s25, 0
	v_add_u32_e32 v67, s11, v66
	v_ashrrev_i32_e32 v68, 13, v67
	v_and_b32_e32 v69, 0x1fff, v67
	v_lshlrev_b32_e32 v69, 3, v69
	v_lshl_add_u32 v62, v68, 21, v69
	global_load_dwordx2 v[0:1], v62, s[12:13] nt
	v_add_u32_e32 v71, 0x10000, v62
	global_load_dwordx2 v[2:3], v71, s[12:13] nt
	v_add_u32_e32 v63, 0x20000, v62
	global_load_dwordx2 v[4:5], v63, s[12:13] nt
	v_add_u32_e32 v71, 0x30000, v62
	global_load_dwordx2 v[6:7], v71, s[12:13] nt
	v_add_u32_e32 v63, 0x40000, v62
	global_load_dwordx2 v[8:9], v63, s[12:13] nt
	v_add_u32_e32 v71, 0x50000, v62
	global_load_dwordx2 v[10:11], v71, s[12:13] nt
	v_add_u32_e32 v63, 0x60000, v62
	global_load_dwordx2 v[12:13], v63, s[12:13] nt
	v_add_u32_e32 v71, 0x70000, v62
	global_load_dwordx2 v[14:15], v71, s[12:13] nt
	v_add_u32_e32 v63, 0x80000, v62
	global_load_dwordx2 v[16:17], v63, s[12:13] nt
	v_add_u32_e32 v71, 0x90000, v62
	global_load_dwordx2 v[18:19], v71, s[12:13] nt
	v_add_u32_e32 v63, 0xa0000, v62
	global_load_dwordx2 v[20:21], v63, s[12:13] nt
	v_add_u32_e32 v71, 0xb0000, v62
	global_load_dwordx2 v[22:23], v71, s[12:13] nt
	v_add_u32_e32 v63, 0xc0000, v62
	global_load_dwordx2 v[24:25], v63, s[12:13] nt
	v_add_u32_e32 v71, 0xd0000, v62
	global_load_dwordx2 v[26:27], v71, s[12:13] nt
	v_add_u32_e32 v63, 0xe0000, v62
	global_load_dwordx2 v[28:29], v63, s[12:13] nt
	v_add_u32_e32 v71, 0xf0000, v62
	global_load_dwordx2 v[30:31], v71, s[12:13] nt
	v_add_u32_e32 v63, 0x100000, v62
	global_load_dwordx2 v[32:33], v63, s[12:13] nt
	v_add_u32_e32 v71, 0x110000, v62
	global_load_dwordx2 v[34:35], v71, s[12:13] nt
	v_add_u32_e32 v63, 0x120000, v62
	global_load_dwordx2 v[36:37], v63, s[12:13] nt
	v_add_u32_e32 v71, 0x130000, v62
	global_load_dwordx2 v[38:39], v71, s[12:13] nt
	v_add_u32_e32 v63, 0x140000, v62
	global_load_dwordx2 v[40:41], v63, s[12:13] nt
	v_add_u32_e32 v71, 0x150000, v62
	global_load_dwordx2 v[42:43], v71, s[12:13] nt
	v_add_u32_e32 v63, 0x160000, v62
	global_load_dwordx2 v[44:45], v63, s[12:13] nt
	v_add_u32_e32 v71, 0x170000, v62
	global_load_dwordx2 v[46:47], v71, s[12:13] nt
	v_add_u32_e32 v63, 0x180000, v62
	global_load_dwordx2 v[48:49], v63, s[12:13] nt
	v_add_u32_e32 v71, 0x190000, v62
	global_load_dwordx2 v[50:51], v71, s[12:13] nt
	v_add_u32_e32 v63, 0x1a0000, v62
	global_load_dwordx2 v[52:53], v63, s[12:13] nt
	v_add_u32_e32 v71, 0x1b0000, v62
	global_load_dwordx2 v[54:55], v71, s[12:13] nt
	v_add_u32_e32 v63, 0x1c0000, v62
	global_load_dwordx2 v[56:57], v63, s[12:13] nt
	v_add_u32_e32 v71, 0x1d0000, v62
	global_load_dwordx2 v[58:59], v71, s[12:13] nt
	v_add_u32_e32 v63, 0x1e0000, v62
	global_load_dwordx2 v[60:61], v63, s[12:13] nt
	s_branch .LBB0_791
.Lidle_p2:
	s_add_u32 s12, s24, 0x1dbf0000
	s_addc_u32 s13, s25, 0
	v_add_u32_e32 v67, s11, v66
	v_ashrrev_i32_e32 v68, 13, v67
	v_and_b32_e32 v69, 0x1fff, v67
	v_lshlrev_b32_e32 v69, 2, v69
	v_lshl_add_u32 v63, v68, 20, v69
	v_and_b32_e32 v68, 3, v68
	v_mov_b32_e32 v70, 0x3c8cc36a
	v_mov_b32_e32 v71, 0x3e08698f
	v_cmp_eq_u32_e32 vcc, 1, v68
	s_nop 1
	v_cndmask_b32_e32 v70, v70, v71, vcc
	v_cmp_eq_u32_e32 vcc, 2, v68
	s_nop 1
	v_cndmask_b32_e32 v70, v70, v236, vcc
	v_cmp_eq_u32_e32 vcc, 3, v68
	s_nop 1
	v_cndmask_b32_e32 v70, v70, v229, vcc
	v_mov_b32_e32 v64, 0
	v_mov_b32_e32 v65, 0
	v_mov_b32_e32 v71, 0
	s_waitcnt vmcnt(0)
	global_store_dword v63, v71, s[12:13]
	v_fma_f32 v64, v70, v64, v0
	v_fma_f32 v65, v70, v65, v1
	v_add_u32_e32 v63, 0x8000, v63
	v_cvt_pk_bf16_f32 v72, v64, v65
	global_store_dword v63, v72, s[12:13]
	v_fma_f32 v64, v70, v64, v2
	v_fma_f32 v65, v70, v65, v3
	v_add_u32_e32 v63, 0x8000, v63
	v_cvt_pk_bf16_f32 v71, v64, v65
	global_store_dword v63, v71, s[12:13]
	v_fma_f32 v64, v70, v64, v4
	v_fma_f32 v65, v70, v65, v5
	v_add_u32_e32 v63, 0x8000, v63
	v_cvt_pk_bf16_f32 v72, v64, v65
	global_store_dword v63, v72, s[12:13]
	v_fma_f32 v64, v70, v64, v6
	v_fma_f32 v65, v70, v65, v7
	v_add_u32_e32 v63, 0x8000, v63
	v_cvt_pk_bf16_f32 v71, v64, v65
	global_store_dword v63, v71, s[12:13]
	v_fma_f32 v64, v70, v64, v8
	v_fma_f32 v65, v70, v65, v9
	v_add_u32_e32 v63, 0x8000, v63
	v_cvt_pk_bf16_f32 v72, v64, v65
	global_store_dword v63, v72, s[12:13]
	v_fma_f32 v64, v70, v64, v10
	v_fma_f32 v65, v70, v65, v11
	v_add_u32_e32 v63, 0x8000, v63
	v_cvt_pk_bf16_f32 v71, v64, v65
	global_store_dword v63, v71, s[12:13]
	v_fma_f32 v64, v70, v64, v12
	v_fma_f32 v65, v70, v65, v13
	v_add_u32_e32 v63, 0x8000, v63
	v_cvt_pk_bf16_f32 v72, v64, v65
	global_store_dword v63, v72, s[12:13]
	v_fma_f32 v64, v70, v64, v14
	v_fma_f32 v65, v70, v65, v15
	v_add_u32_e32 v63, 0x8000, v63
	v_cvt_pk_bf16_f32 v71, v64, v65
	global_store_dword v63, v71, s[12:13]
	v_fma_f32 v64, v70, v64, v16
	v_fma_f32 v65, v70, v65, v17
	v_add_u32_e32 v63, 0x8000, v63
	v_cvt_pk_bf16_f32 v72, v64, v65
	global_store_dword v63, v72, s[12:13]
	v_fma_f32 v64, v70, v64, v18
	v_fma_f32 v65, v70, v65, v19
	v_add_u32_e32 v63, 0x8000, v63
	v_cvt_pk_bf16_f32 v71, v64, v65
	global_store_dword v63, v71, s[12:13]
	v_fma_f32 v64, v70, v64, v20
	v_fma_f32 v65, v70, v65, v21
	v_add_u32_e32 v63, 0x8000, v63
	v_cvt_pk_bf16_f32 v72, v64, v65
	global_store_dword v63, v72, s[12:13]
	v_fma_f32 v64, v70, v64, v22
	v_fma_f32 v65, v70, v65, v23
	v_add_u32_e32 v63, 0x8000, v63
	v_cvt_pk_bf16_f32 v71, v64, v65
	global_store_dword v63, v71, s[12:13]
	v_fma_f32 v64, v70, v64, v24
	v_fma_f32 v65, v70, v65, v25
	v_add_u32_e32 v63, 0x8000, v63
	v_cvt_pk_bf16_f32 v72, v64, v65
	global_store_dword v63, v72, s[12:13]
	v_fma_f32 v64, v70, v64, v26
	v_fma_f32 v65, v70, v65, v27
	v_add_u32_e32 v63, 0x8000, v63
	v_cvt_pk_bf16_f32 v71, v64, v65
	global_store_dword v63, v71, s[12:13]
	v_fma_f32 v64, v70, v64, v28
	v_fma_f32 v65, v70, v65, v29
	v_add_u32_e32 v63, 0x8000, v63
	v_cvt_pk_bf16_f32 v72, v64, v65
	global_store_dword v63, v72, s[12:13]
	v_fma_f32 v64, v70, v64, v30
	v_fma_f32 v65, v70, v65, v31
	v_add_u32_e32 v63, 0x8000, v63
	v_cvt_pk_bf16_f32 v71, v64, v65
	global_store_dword v63, v71, s[12:13]
	v_fma_f32 v64, v70, v64, v32
	v_fma_f32 v65, v70, v65, v33
	v_add_u32_e32 v63, 0x8000, v63
	v_cvt_pk_bf16_f32 v72, v64, v65
	global_store_dword v63, v72, s[12:13]
	v_fma_f32 v64, v70, v64, v34
	v_fma_f32 v65, v70, v65, v35
	v_add_u32_e32 v63, 0x8000, v63
	v_cvt_pk_bf16_f32 v71, v64, v65
	global_store_dword v63, v71, s[12:13]
	v_fma_f32 v64, v70, v64, v36
	v_fma_f32 v65, v70, v65, v37
	v_add_u32_e32 v63, 0x8000, v63
	v_cvt_pk_bf16_f32 v72, v64, v65
	global_store_dword v63, v72, s[12:13]
	v_fma_f32 v64, v70, v64, v38
	v_fma_f32 v65, v70, v65, v39
	v_add_u32_e32 v63, 0x8000, v63
	v_cvt_pk_bf16_f32 v71, v64, v65
	global_store_dword v63, v71, s[12:13]
	v_fma_f32 v64, v70, v64, v40
	v_fma_f32 v65, v70, v65, v41
	v_add_u32_e32 v63, 0x8000, v63
	v_cvt_pk_bf16_f32 v72, v64, v65
	global_store_dword v63, v72, s[12:13]
	v_fma_f32 v64, v70, v64, v42
	v_fma_f32 v65, v70, v65, v43
	v_add_u32_e32 v63, 0x8000, v63
	v_cvt_pk_bf16_f32 v71, v64, v65
	global_store_dword v63, v71, s[12:13]
	v_fma_f32 v64, v70, v64, v44
	v_fma_f32 v65, v70, v65, v45
	v_add_u32_e32 v63, 0x8000, v63
	v_cvt_pk_bf16_f32 v72, v64, v65
	global_store_dword v63, v72, s[12:13]
	v_fma_f32 v64, v70, v64, v46
	v_fma_f32 v65, v70, v65, v47
	v_add_u32_e32 v63, 0x8000, v63
	v_cvt_pk_bf16_f32 v71, v64, v65
	global_store_dword v63, v71, s[12:13]
	v_fma_f32 v64, v70, v64, v48
	v_fma_f32 v65, v70, v65, v49
	v_add_u32_e32 v63, 0x8000, v63
	v_cvt_pk_bf16_f32 v72, v64, v65
	global_store_dword v63, v72, s[12:13]
	v_fma_f32 v64, v70, v64, v50
	v_fma_f32 v65, v70, v65, v51
	v_add_u32_e32 v63, 0x8000, v63
	v_cvt_pk_bf16_f32 v71, v64, v65
	global_store_dword v63, v71, s[12:13]
	v_fma_f32 v64, v70, v64, v52
	v_fma_f32 v65, v70, v65, v53
	v_add_u32_e32 v63, 0x8000, v63
	v_cvt_pk_bf16_f32 v72, v64, v65
	global_store_dword v63, v72, s[12:13]
	v_fma_f32 v64, v70, v64, v54
	v_fma_f32 v65, v70, v65, v55
	v_add_u32_e32 v63, 0x8000, v63
	v_cvt_pk_bf16_f32 v71, v64, v65
	global_store_dword v63, v71, s[12:13]
	v_fma_f32 v64, v70, v64, v56
	v_fma_f32 v65, v70, v65, v57
	v_add_u32_e32 v63, 0x8000, v63
	v_cvt_pk_bf16_f32 v72, v64, v65
	global_store_dword v63, v72, s[12:13]
	v_fma_f32 v64, v70, v64, v58
	v_fma_f32 v65, v70, v65, v59
	v_add_u32_e32 v63, 0x8000, v63
	v_cvt_pk_bf16_f32 v71, v64, v65
	global_store_dword v63, v71, s[12:13]
	v_fma_f32 v64, v70, v64, v60
	v_fma_f32 v65, v70, v65, v61
	v_add_u32_e32 v63, 0x8000, v63
	v_cvt_pk_bf16_f32 v72, v64, v65
	global_store_dword v63, v72, s[12:13]
	s_branch .LBB0_791
